# rowpass loop rewritten: all loads of a row issued together, next row prefetched, gains held in registers
# speedup vs baseline: 1.0429x; 1.0028x over previous
; __device__ __forceinline__ float bflo(unsigned w) { return __uint_as_float(w << 16); }
; __device__ __forceinline__ float bfhi(unsigned w) { return __uint_as_float(w & 0xffff0000u); }
; #define LIDS const int tid_l = TID(), bid_l = BID(), gdim_l = GDIM(); (void)tid_l; (void)bid_l; (void)gdim_l;
; __device__ __forceinline__ void rowpass(int wv, const float* xin, const bf16_t* outb, const float* g_post, const float* g_pre_next, float* xres, bf16_t* xn, int mode) { LIDS
;     const int lane = tid_l & 63, wid = tid_l >> 6;
;     ...
;     for (int row = bid_l * 8 + wid; row < SEQ; row += gdim_l * 8) {
;         f32x4 xv[8]; float ss = 0.f;
;         if (mode == 0) {
; #pragma unroll
;             for (int i = 0; i < 8; ++i) xv[i] = __builtin_nontemporal_load((const f32x4*)(xin + (size_t)row * DM + RP_OFF(i)));
;         } else {
;             f32x4 ov[8]; float so = 0.f;
; #pragma unroll
;             for (int ip = 0; ip < 4; ++ip) { const u32x4 w = __builtin_nontemporal_load((const u32x4*)(outb + (size_t)row * DM + ip * 512 + lane * 8));
;                 ov[2 * ip][0] = bflo(w[0]); ov[2 * ip][1] = bfhi(w[0]); ov[2 * ip][2] = bflo(w[1]); ov[2 * ip][3] = bfhi(w[1]);
;                 ov[2 * ip + 1][0] = bflo(w[2]); ov[2 * ip + 1][1] = bfhi(w[2]); ov[2 * ip + 1][2] = bflo(w[3]); ov[2 * ip + 1][3] = bfhi(w[3]); }
; #pragma unroll
;             for (int i = 0; i < 8; ++i) so += ov[i][0] * ov[i][0] + ov[i][1] * ov[i][1] + ov[i][2] * ov[i][2] + ov[i][3] * ov[i][3];
;             so = wave_sum(so); const float inv = rsqrtf(so * (1.0f / DM) + EPS);
; #pragma unroll
;             for (int i = 0; i < 8; ++i) { const f32x4 xo = __builtin_nontemporal_load((const f32x4*)(xin + (size_t)row * DM + RP_OFF(i))); const f32x4 gp = *(const f32x4*)(g_post + RP_OFF(i));
.LBB0_226:
	s_mov_b32 s16, 0x1000
	s_mov_b32 s17, 0
	v_mov_b32_e32 v61, v72
	v_mov_b32_e32 v62, v73
	v_readfirstlane_b32 s0, v67
	v_lshl_add_u64 v[54:55], v[54:55], 0, v[176:177]
	v_lshl_add_u64 v[56:57], v[56:57], 0, v[176:177]
	v_add_co_u32_e32 v32, vcc, 0xee000000, v52
	s_nop 1
	v_addc_co_u32_e32 v33, vcc, -1, v53, vcc
	global_load_dwordx4 v[178:181], v[40:41], off offset:0
	global_load_dwordx4 v[182:185], v[40:41], off offset:16
	global_load_dwordx4 v[186:189], v[40:41], off offset:2048
	global_load_dwordx4 v[190:193], v[40:41], off offset:2064
	global_load_dwordx4 v[194:197], v[42:43], off offset:0
	global_load_dwordx4 v[198:201], v[42:43], off offset:16
	global_load_dwordx4 v[202:205], v[44:45], off offset:0
	global_load_dwordx4 v[206:209], v[44:45], off offset:16
	s_andn2_b64 vcc, exec, s[10:11]
	s_cbranch_vccnz .Lrp_nogq
	global_load_dwordx4 v[218:221], v[46:47], off offset:0
	global_load_dwordx4 v[222:225], v[46:47], off offset:16
	global_load_dwordx4 v[226:229], v[46:47], off offset:2048
	global_load_dwordx4 v[230:233], v[46:47], off offset:2064
	global_load_dwordx4 v[234:237], v[48:49], off offset:0
	global_load_dwordx4 v[238:241], v[48:49], off offset:16
	global_load_dwordx4 v[242:245], v[50:51], off offset:0
	global_load_dwordx4 v[246:249], v[50:51], off offset:16
.Lrp_nogq:
	global_load_dwordx4 v[72:75], v[52:53], off offset:0 nt
	global_load_dwordx4 v[76:79], v[52:53], off offset:1024 nt
	global_load_dwordx4 v[80:83], v[52:53], off offset:2048 nt
	global_load_dwordx4 v[84:87], v[52:53], off offset:3072 nt
	v_lshl_add_u64 v[34:35], v[54:55], 0, s[16:17]
	global_load_dwordx4 v[88:91], v[54:55], off offset:0 nt
	global_load_dwordx4 v[92:95], v[54:55], off offset:16 nt
	global_load_dwordx4 v[96:99], v[54:55], off offset:2048 nt
	global_load_dwordx4 v[100:103], v[54:55], off offset:2064 nt
	global_load_dwordx4 v[104:107], v[34:35], off offset:0 nt
	global_load_dwordx4 v[108:111], v[34:35], off offset:16 nt
	global_load_dwordx4 v[112:115], v[34:35], off offset:2048 nt
	global_load_dwordx4 v[116:119], v[34:35], off offset:2064 nt
	s_mov_b32 s8, 1
.Lrp_loop:
	s_add_i32 s0, s0, s12
	s_cmp_gt_i32 s0, s96
	s_cbranch_scc1 .Lrp_last1
	v_lshl_add_u64 v[52:53], v[52:53], 0, s[62:63]
	v_lshl_add_u64 v[54:55], v[54:55], 0, s[72:73]
	global_load_dwordx4 v[120:123], v[52:53], off offset:0 nt
	global_load_dwordx4 v[124:127], v[52:53], off offset:1024 nt
	global_load_dwordx4 v[128:131], v[52:53], off offset:2048 nt
	global_load_dwordx4 v[132:135], v[52:53], off offset:3072 nt
	v_lshl_add_u64 v[34:35], v[54:55], 0, s[16:17]
	global_load_dwordx4 v[136:139], v[54:55], off offset:0 nt
	global_load_dwordx4 v[140:143], v[54:55], off offset:16 nt
	global_load_dwordx4 v[144:147], v[54:55], off offset:2048 nt
	global_load_dwordx4 v[148:151], v[54:55], off offset:2064 nt
	global_load_dwordx4 v[152:155], v[34:35], off offset:0 nt
	global_load_dwordx4 v[156:159], v[34:35], off offset:16 nt
	global_load_dwordx4 v[160:163], v[34:35], off offset:2048 nt
	global_load_dwordx4 v[164:167], v[34:35], off offset:2064 nt
	s_cmp_lg_u32 s8, 0
	s_cbranch_scc1 .Lrp_f1
	s_waitcnt vmcnt(20)
	s_branch .Lrp_go1
.Lrp_f1:
	s_waitcnt vmcnt(12)
	s_branch .Lrp_go1
.Lrp_last1:
	s_cmp_lg_u32 s8, 0
	s_cbranch_scc1 .Lrp_lf1
	s_waitcnt vmcnt(8)
	s_branch .Lrp_go1

; __device__ __forceinline__ float bflo(unsigned w) { return __uint_as_float(w << 16); }
; __device__ __forceinline__ float bfhi(unsigned w) { return __uint_as_float(w & 0xffff0000u); }
; __device__ __forceinline__ void rowpass(int wv, const float* xin, const bf16_t* outb, const float* g_post, const float* g_pre_next, float* xres, bf16_t* xn, int mode) { LIDS
;     ...
;             f32x4 ov[8]; float so = 0.f;
; #pragma unroll
;             for (int ip = 0; ip < 4; ++ip) { const u32x4 w = __builtin_nontemporal_load((const u32x4*)(outb + (size_t)row * DM + ip * 512 + lane * 8));
;                 ov[2 * ip][0] = bflo(w[0]); ov[2 * ip][1] = bfhi(w[0]); ov[2 * ip][2] = bflo(w[1]); ov[2 * ip][3] = bfhi(w[1]);
;                 ov[2 * ip + 1][0] = bflo(w[2]); ov[2 * ip + 1][1] = bfhi(w[2]); ov[2 * ip + 1][2] = bflo(w[3]); ov[2 * ip + 1][3] = bfhi(w[3]); }
; #pragma unroll
;             for (int i = 0; i < 8; ++i) so += ov[i][0] * ov[i][0] + ov[i][1] * ov[i][1] + ov[i][2] * ov[i][2] + ov[i][3] * ov[i][3];
;             so = wave_sum(so); const float inv = rsqrtf(so * (1.0f / DM) + EPS);
; #pragma unroll
;             for (int i = 0; i < 8; ++i) { const f32x4 xo = __builtin_nontemporal_load((const f32x4*)(xin + (size_t)row * DM + RP_OFF(i))); const f32x4 gp = *(const f32x4*)(g_post + RP_OFF(i));
;                 xv[i] = xo + ov[i] * inv * gp; }
;         }
; #pragma unroll
;         for (int i = 0; i < 8; ++i) { if (mode != 0) __builtin_nontemporal_store(xv[i], (f32x4*)(xres + (size_t)row * DM + RP_OFF(i)));
;             ss += xv[i][0] * xv[i][0] + xv[i][1] * xv[i][1] + xv[i][2] * xv[i][2] + xv[i][3] * xv[i][3]; }
.Lrp_go1:
	s_mov_b32 s8, 0
	v_lshlrev_b32_e32 v0, 16, v72
	v_and_b32_e32 v1, 0xffff0000, v72
	v_lshlrev_b32_e32 v2, 16, v73
	v_and_b32_e32 v3, 0xffff0000, v73
	v_lshlrev_b32_e32 v4, 16, v74
	v_and_b32_e32 v5, 0xffff0000, v74
	v_lshlrev_b32_e32 v6, 16, v75
	v_and_b32_e32 v7, 0xffff0000, v75
	v_lshlrev_b32_e32 v8, 16, v76
	v_and_b32_e32 v9, 0xffff0000, v76
	v_lshlrev_b32_e32 v10, 16, v77
	v_and_b32_e32 v11, 0xffff0000, v77
	v_lshlrev_b32_e32 v12, 16, v78
	v_and_b32_e32 v13, 0xffff0000, v78
	v_lshlrev_b32_e32 v14, 16, v79
	v_and_b32_e32 v15, 0xffff0000, v79
	v_lshlrev_b32_e32 v16, 16, v80
	v_and_b32_e32 v17, 0xffff0000, v80
	v_lshlrev_b32_e32 v18, 16, v81
	v_and_b32_e32 v19, 0xffff0000, v81
	v_lshlrev_b32_e32 v20, 16, v82
	v_and_b32_e32 v21, 0xffff0000, v82
	v_lshlrev_b32_e32 v22, 16, v83
	v_and_b32_e32 v23, 0xffff0000, v83
	v_lshlrev_b32_e32 v24, 16, v84
	v_and_b32_e32 v25, 0xffff0000, v84
	v_lshlrev_b32_e32 v26, 16, v85
	v_and_b32_e32 v27, 0xffff0000, v85
	v_lshlrev_b32_e32 v28, 16, v86
	v_and_b32_e32 v29, 0xffff0000, v86
	v_lshlrev_b32_e32 v30, 16, v87
	v_and_b32_e32 v31, 0xffff0000, v87
	v_mul_f32_e32 v36, v0, v0
	v_mul_f32_e32 v37, v1, v1
	v_mul_f32_e32 v38, v2, v2
	v_mul_f32_e32 v39, v3, v3
	v_fmac_f32_e32 v36, v4, v4
	v_fmac_f32_e32 v37, v5, v5
	v_fmac_f32_e32 v38, v6, v6
	v_fmac_f32_e32 v39, v7, v7
	v_fmac_f32_e32 v36, v8, v8
	v_fmac_f32_e32 v37, v9, v9
	v_fmac_f32_e32 v38, v10, v10
	v_fmac_f32_e32 v39, v11, v11
	v_fmac_f32_e32 v36, v12, v12
	v_fmac_f32_e32 v37, v13, v13
	v_fmac_f32_e32 v38, v14, v14
	v_fmac_f32_e32 v39, v15, v15
	v_fmac_f32_e32 v36, v16, v16
	v_fmac_f32_e32 v37, v17, v17
	v_fmac_f32_e32 v38, v18, v18
	v_fmac_f32_e32 v39, v19, v19
	v_fmac_f32_e32 v36, v20, v20
	v_fmac_f32_e32 v37, v21, v21
	v_fmac_f32_e32 v38, v22, v22
	v_fmac_f32_e32 v39, v23, v23
	v_fmac_f32_e32 v36, v24, v24
	v_fmac_f32_e32 v37, v25, v25
	v_fmac_f32_e32 v38, v26, v26
	v_fmac_f32_e32 v39, v27, v27
	v_fmac_f32_e32 v36, v28, v28
	v_fmac_f32_e32 v37, v29, v29
	v_fmac_f32_e32 v38, v30, v30
	v_fmac_f32_e32 v39, v31, v31
	v_add_f32_e32 v36, v36, v37
	v_add_f32_e32 v38, v38, v39
	v_add_f32_e32 v58, v36, v38
	ds_bpermute_b32 v59, v68, v58
	s_waitcnt lgkmcnt(0)
	v_add_f32_e32 v58, v58, v59
	ds_bpermute_b32 v59, v69, v58
	s_waitcnt lgkmcnt(0)
	v_add_f32_e32 v58, v58, v59
	ds_bpermute_b32 v59, v70, v58
	s_waitcnt lgkmcnt(0)
	v_add_f32_e32 v58, v58, v59
	ds_bpermute_b32 v59, v71, v58
	s_waitcnt lgkmcnt(0)
	v_add_f32_e32 v58, v58, v59
	ds_bpermute_b32 v59, v61, v58
	s_waitcnt lgkmcnt(0)
	v_add_f32_e32 v58, v58, v59
	ds_bpermute_b32 v59, v62, v58
	s_waitcnt lgkmcnt(0)
	v_add_f32_e32 v58, v58, v59
	v_fmamk_f32 v60, v58, 0x3a000000, v252
	v_rsq_f32_e32 v60, v60
	s_nop 0
	v_mul_f32_e32 v0, v0, v60
	v_mul_f32_e32 v1, v1, v60
	v_mul_f32_e32 v2, v2, v60
	v_mul_f32_e32 v3, v3, v60
	v_mul_f32_e32 v4, v4, v60
	v_mul_f32_e32 v5, v5, v60
	v_mul_f32_e32 v6, v6, v60
	v_mul_f32_e32 v7, v7, v60
	v_mul_f32_e32 v8, v8, v60
	v_mul_f32_e32 v9, v9, v60
	v_mul_f32_e32 v10, v10, v60
	v_mul_f32_e32 v11, v11, v60
	v_mul_f32_e32 v12, v12, v60
	v_mul_f32_e32 v13, v13, v60
	v_mul_f32_e32 v14, v14, v60
	v_mul_f32_e32 v15, v15, v60
	v_mul_f32_e32 v16, v16, v60
	v_mul_f32_e32 v17, v17, v60
	v_mul_f32_e32 v18, v18, v60
	v_mul_f32_e32 v19, v19, v60
	v_mul_f32_e32 v20, v20, v60
	v_mul_f32_e32 v21, v21, v60
	v_mul_f32_e32 v22, v22, v60
	v_mul_f32_e32 v23, v23, v60
	v_mul_f32_e32 v24, v24, v60
	v_mul_f32_e32 v25, v25, v60
	v_mul_f32_e32 v26, v26, v60
	v_mul_f32_e32 v27, v27, v60
	v_mul_f32_e32 v28, v28, v60
	v_mul_f32_e32 v29, v29, v60
	v_mul_f32_e32 v30, v30, v60
	v_mul_f32_e32 v31, v31, v60
	v_fmac_f32_e32 v88, v178, v0
	v_fmac_f32_e32 v89, v179, v1
	v_fmac_f32_e32 v90, v180, v2
	v_fmac_f32_e32 v91, v181, v3
	v_fmac_f32_e32 v92, v182, v4
	v_fmac_f32_e32 v93, v183, v5
	v_fmac_f32_e32 v94, v184, v6
	v_fmac_f32_e32 v95, v185, v7
	v_fmac_f32_e32 v96, v186, v8
	v_fmac_f32_e32 v97, v187, v9
	v_fmac_f32_e32 v98, v188, v10
	v_fmac_f32_e32 v99, v189, v11
	v_fmac_f32_e32 v100, v190, v12
	v_fmac_f32_e32 v101, v191, v13
	v_fmac_f32_e32 v102, v192, v14
	v_fmac_f32_e32 v103, v193, v15
	v_fmac_f32_e32 v104, v194, v16
	v_fmac_f32_e32 v105, v195, v17
	v_fmac_f32_e32 v106, v196, v18
	v_fmac_f32_e32 v107, v197, v19
	v_fmac_f32_e32 v108, v198, v20
	v_fmac_f32_e32 v109, v199, v21
	v_fmac_f32_e32 v110, v200, v22
	v_fmac_f32_e32 v111, v201, v23
	v_fmac_f32_e32 v112, v202, v24
	v_fmac_f32_e32 v113, v203, v25
	v_fmac_f32_e32 v114, v204, v26
	v_fmac_f32_e32 v115, v205, v27
	v_fmac_f32_e32 v116, v206, v28
	v_fmac_f32_e32 v117, v207, v29
	v_fmac_f32_e32 v118, v208, v30
	v_fmac_f32_e32 v119, v209, v31
	v_lshl_add_u64 v[34:35], v[56:57], 0, s[16:17]
	global_store_dwordx4 v[56:57], v[88:91], off offset:0 nt
	global_store_dwordx4 v[56:57], v[92:95], off offset:16 nt
	global_store_dwordx4 v[56:57], v[96:99], off offset:2048 nt
	global_store_dwordx4 v[56:57], v[100:103], off offset:2064 nt
	global_store_dwordx4 v[34:35], v[104:107], off offset:0 nt
	global_store_dwordx4 v[34:35], v[108:111], off offset:16 nt
	global_store_dwordx4 v[34:35], v[112:115], off offset:2048 nt
	global_store_dwordx4 v[34:35], v[116:119], off offset:2064 nt
	v_lshl_add_u64 v[56:57], v[56:57], 0, s[72:73]
	s_andn2_b64 vcc, exec, s[10:11]
	s_cbranch_vccnz .Lrp_nopre1
; __device__ __forceinline__ float bflo(unsigned w) { return __uint_as_float(w << 16); }
; __device__ __forceinline__ void rowpass(int wv, const float* xin, const bf16_t* outb, const float* g_post, const float* g_pre_next, float* xres, bf16_t* xn, int mode) { LIDS
;     ...
;     for (int row = bid_l * 8 + wid; row < SEQ; row += gdim_l * 8) {
;         f32x4 xv[8]; float ss = 0.f;
;         if (mode == 0) {
; #pragma unroll
;             for (int i = 0; i < 8; ++i) xv[i] = __builtin_nontemporal_load((const f32x4*)(xin + (size_t)row * DM + RP_OFF(i)));
;         } else {
;             f32x4 ov[8]; float so = 0.f;
; #pragma unroll
;             for (int ip = 0; ip < 4; ++ip) { const u32x4 w = __builtin_nontemporal_load((const u32x4*)(outb + (size_t)row * DM + ip * 512 + lane * 8));
;                 ov[2 * ip][0] = bflo(w[0]); ov[2 * ip][1] = bfhi(w[0]); ov[2 * ip][2] = bflo(w[1]); ov[2 * ip][3] = bfhi(w[1]);
;                 ov[2 * ip + 1][0] = bflo(w[2]); ov[2 * ip + 1][1] = bfhi(w[2]); ov[2 * ip + 1][2] = bflo(w[3]); ov[2 * ip + 1][3] = bfhi(w[3]); }
; #pragma unroll
;             for (int i = 0; i < 8; ++i) so += ov[i][0] * ov[i][0] + ov[i][1] * ov[i][1] + ov[i][2] * ov[i][2] + ov[i][3] * ov[i][3];
;             so = wave_sum(so); const float inv = rsqrtf(so * (1.0f / DM) + EPS);
; #pragma unroll
;             for (int i = 0; i < 8; ++i) { const f32x4 xo = __builtin_nontemporal_load((const f32x4*)(xin + (size_t)row * DM + RP_OFF(i))); const f32x4 gp = *(const f32x4*)(g_post + RP_OFF(i));
;                 xv[i] = xo + ov[i] * inv * gp; }
;         }
; #pragma unroll
;         for (int i = 0; i < 8; ++i) { if (mode != 0) __builtin_nontemporal_store(xv[i], (f32x4*)(xres + (size_t)row * DM + RP_OFF(i)));
;             ss += xv[i][0] * xv[i][0] + xv[i][1] * xv[i][1] + xv[i][2] * xv[i][2] + xv[i][3] * xv[i][3]; }
;         if (g_pre_next) {
;             ss = wave_sum(ss); const float inv = rsqrtf(ss * (1.0f / DM) + EPS);
; #pragma unroll
;             for (int ip = 0; ip < 4; ++ip) { const f32x4 g0 = *(const f32x4*)(g_pre_next + RP_OFF(2 * ip)), g1 = *(const f32x4*)(g_pre_next + RP_OFF(2 * ip + 1));
;                 const f32x4 y0 = xv[2 * ip] * inv * g0, y1 = xv[2 * ip + 1] * inv * g1;
;                 *(u32x4*)(xn + (size_t)row * DM + ip * 512 + lane * 8) = pack8(y0, y1); }
;         }
	v_mul_f32_e32 v36, v88, v88
	v_mul_f32_e32 v37, v89, v89
	v_mul_f32_e32 v38, v90, v90
	v_mul_f32_e32 v39, v91, v91
	v_fmac_f32_e32 v36, v92, v92
	v_fmac_f32_e32 v37, v93, v93
	v_fmac_f32_e32 v38, v94, v94
	v_fmac_f32_e32 v39, v95, v95
	v_fmac_f32_e32 v36, v96, v96
	v_fmac_f32_e32 v37, v97, v97
	v_fmac_f32_e32 v38, v98, v98
	v_fmac_f32_e32 v39, v99, v99
	v_fmac_f32_e32 v36, v100, v100
	v_fmac_f32_e32 v37, v101, v101
	v_fmac_f32_e32 v38, v102, v102
	v_fmac_f32_e32 v39, v103, v103
	v_fmac_f32_e32 v36, v104, v104
	v_fmac_f32_e32 v37, v105, v105
	v_fmac_f32_e32 v38, v106, v106
	v_fmac_f32_e32 v39, v107, v107
	v_fmac_f32_e32 v36, v108, v108
	v_fmac_f32_e32 v37, v109, v109
	v_fmac_f32_e32 v38, v110, v110
	v_fmac_f32_e32 v39, v111, v111
	v_fmac_f32_e32 v36, v112, v112
	v_fmac_f32_e32 v37, v113, v113
	v_fmac_f32_e32 v38, v114, v114
	v_fmac_f32_e32 v39, v115, v115
	v_fmac_f32_e32 v36, v116, v116
	v_fmac_f32_e32 v37, v117, v117
	v_fmac_f32_e32 v38, v118, v118
	v_fmac_f32_e32 v39, v119, v119
	v_add_f32_e32 v36, v36, v37
	v_add_f32_e32 v38, v38, v39
	v_add_f32_e32 v58, v36, v38
	ds_bpermute_b32 v59, v68, v58
	s_waitcnt lgkmcnt(0)
	v_add_f32_e32 v58, v58, v59
	ds_bpermute_b32 v59, v69, v58
	s_waitcnt lgkmcnt(0)
	v_add_f32_e32 v58, v58, v59
	ds_bpermute_b32 v59, v70, v58
	s_waitcnt lgkmcnt(0)
	v_add_f32_e32 v58, v58, v59
	ds_bpermute_b32 v59, v71, v58
	s_waitcnt lgkmcnt(0)
	v_add_f32_e32 v58, v58, v59
	ds_bpermute_b32 v59, v61, v58
	s_waitcnt lgkmcnt(0)
	v_add_f32_e32 v58, v58, v59
	ds_bpermute_b32 v59, v62, v58
	s_waitcnt lgkmcnt(0)
	v_add_f32_e32 v58, v58, v59
	v_fmamk_f32 v60, v58, 0x3a000000, v252
	v_rsq_f32_e32 v60, v60
	s_nop 0
	v_mul_f32_e32 v168, v88, v60
	v_mul_f32_e32 v169, v89, v60
	v_mul_f32_e32 v170, v90, v60
	v_mul_f32_e32 v171, v91, v60
	v_mul_f32_e32 v172, v92, v60
	v_mul_f32_e32 v173, v93, v60
	v_mul_f32_e32 v174, v94, v60
	v_mul_f32_e32 v175, v95, v60
	v_mul_f32_e32 v168, v168, v218
	v_mul_f32_e32 v169, v169, v219
	v_mul_f32_e32 v170, v170, v220
	v_mul_f32_e32 v171, v171, v221
	v_mul_f32_e32 v172, v172, v222
	v_mul_f32_e32 v173, v173, v223
	v_mul_f32_e32 v174, v174, v224
	v_mul_f32_e32 v175, v175, v225
	v_cvt_pk_bf16_f32 v72, v168, v169
	v_cvt_pk_bf16_f32 v73, v170, v171
	v_cvt_pk_bf16_f32 v74, v172, v173
	v_cvt_pk_bf16_f32 v75, v174, v175
	v_mul_f32_e32 v168, v96, v60
	v_mul_f32_e32 v169, v97, v60
	v_mul_f32_e32 v170, v98, v60
	v_mul_f32_e32 v171, v99, v60
	v_mul_f32_e32 v172, v100, v60
	v_mul_f32_e32 v173, v101, v60
	v_mul_f32_e32 v174, v102, v60
	v_mul_f32_e32 v175, v103, v60
	v_mul_f32_e32 v168, v168, v226
	v_mul_f32_e32 v169, v169, v227
	v_mul_f32_e32 v170, v170, v228
	v_mul_f32_e32 v171, v171, v229
	v_mul_f32_e32 v172, v172, v230
	v_mul_f32_e32 v173, v173, v231
	v_mul_f32_e32 v174, v174, v232
	v_mul_f32_e32 v175, v175, v233
	v_cvt_pk_bf16_f32 v76, v168, v169
	v_cvt_pk_bf16_f32 v77, v170, v171
	v_cvt_pk_bf16_f32 v78, v172, v173
	v_cvt_pk_bf16_f32 v79, v174, v175
	v_mul_f32_e32 v168, v104, v60
	v_mul_f32_e32 v169, v105, v60
	v_mul_f32_e32 v170, v106, v60
	v_mul_f32_e32 v171, v107, v60
	v_mul_f32_e32 v172, v108, v60
	v_mul_f32_e32 v173, v109, v60
	v_mul_f32_e32 v174, v110, v60
	v_mul_f32_e32 v175, v111, v60
	v_mul_f32_e32 v168, v168, v234
	v_mul_f32_e32 v169, v169, v235
	v_mul_f32_e32 v170, v170, v236
	v_mul_f32_e32 v171, v171, v237
	v_mul_f32_e32 v172, v172, v238
	v_mul_f32_e32 v173, v173, v239
	v_mul_f32_e32 v174, v174, v240
	v_mul_f32_e32 v175, v175, v241
	v_cvt_pk_bf16_f32 v80, v168, v169
	v_cvt_pk_bf16_f32 v81, v170, v171
	v_cvt_pk_bf16_f32 v82, v172, v173
	v_cvt_pk_bf16_f32 v83, v174, v175
	v_mul_f32_e32 v168, v112, v60
	v_mul_f32_e32 v169, v113, v60
	v_mul_f32_e32 v170, v114, v60
	v_mul_f32_e32 v171, v115, v60
	v_mul_f32_e32 v172, v116, v60
	v_mul_f32_e32 v173, v117, v60
	v_mul_f32_e32 v174, v118, v60
	v_mul_f32_e32 v175, v119, v60
	v_mul_f32_e32 v168, v168, v242
	v_mul_f32_e32 v169, v169, v243
	v_mul_f32_e32 v170, v170, v244
	v_mul_f32_e32 v171, v171, v245
	v_mul_f32_e32 v172, v172, v246
	v_mul_f32_e32 v173, v173, v247
	v_mul_f32_e32 v174, v174, v248
	v_mul_f32_e32 v175, v175, v249
	v_cvt_pk_bf16_f32 v84, v168, v169
	v_cvt_pk_bf16_f32 v85, v170, v171
	v_cvt_pk_bf16_f32 v86, v172, v173
	v_cvt_pk_bf16_f32 v87, v174, v175
	global_store_dwordx4 v[32:33], v[72:75], off offset:0
	global_store_dwordx4 v[32:33], v[76:79], off offset:1024
	global_store_dwordx4 v[32:33], v[80:83], off offset:2048
	global_store_dwordx4 v[32:33], v[84:87], off offset:3072
	v_lshl_add_u64 v[32:33], v[32:33], 0, s[62:63]
.Lrp_nopre1:
	s_cmp_gt_i32 s0, s96
	s_cbranch_scc1 .Lrp_done
	s_add_i32 s0, s0, s12
	s_cmp_gt_i32 s0, s96
	s_cbranch_scc1 .Lrp_last2
	v_lshl_add_u64 v[52:53], v[52:53], 0, s[62:63]
	v_lshl_add_u64 v[54:55], v[54:55], 0, s[72:73]
	global_load_dwordx4 v[72:75], v[52:53], off offset:0 nt
	global_load_dwordx4 v[76:79], v[52:53], off offset:1024 nt
	global_load_dwordx4 v[80:83], v[52:53], off offset:2048 nt
	global_load_dwordx4 v[84:87], v[52:53], off offset:3072 nt
	v_lshl_add_u64 v[34:35], v[54:55], 0, s[16:17]
	global_load_dwordx4 v[88:91], v[54:55], off offset:0 nt
	global_load_dwordx4 v[92:95], v[54:55], off offset:16 nt
	global_load_dwordx4 v[96:99], v[54:55], off offset:2048 nt
	global_load_dwordx4 v[100:103], v[54:55], off offset:2064 nt
	global_load_dwordx4 v[104:107], v[34:35], off offset:0 nt
	global_load_dwordx4 v[108:111], v[34:35], off offset:16 nt
	global_load_dwordx4 v[112:115], v[34:35], off offset:2048 nt
	global_load_dwordx4 v[116:119], v[34:35], off offset:2064 nt
	s_cmp_lg_u32 s8, 0
	s_cbranch_scc1 .Lrp_f2
	s_waitcnt vmcnt(20)
	s_branch .Lrp_go2

; __device__ __forceinline__ float bflo(unsigned w) { return __uint_as_float(w << 16); }
; __device__ __forceinline__ float bfhi(unsigned w) { return __uint_as_float(w & 0xffff0000u); }
; __device__ __forceinline__ void rowpass(int wv, const float* xin, const bf16_t* outb, const float* g_post, const float* g_pre_next, float* xres, bf16_t* xn, int mode) { LIDS
;     ...
;             f32x4 ov[8]; float so = 0.f;
; #pragma unroll
;             for (int ip = 0; ip < 4; ++ip) { const u32x4 w = __builtin_nontemporal_load((const u32x4*)(outb + (size_t)row * DM + ip * 512 + lane * 8));
;                 ov[2 * ip][0] = bflo(w[0]); ov[2 * ip][1] = bfhi(w[0]); ov[2 * ip][2] = bflo(w[1]); ov[2 * ip][3] = bfhi(w[1]);
;                 ov[2 * ip + 1][0] = bflo(w[2]); ov[2 * ip + 1][1] = bfhi(w[2]); ov[2 * ip + 1][2] = bflo(w[3]); ov[2 * ip + 1][3] = bfhi(w[3]); }
; #pragma unroll
;             for (int i = 0; i < 8; ++i) so += ov[i][0] * ov[i][0] + ov[i][1] * ov[i][1] + ov[i][2] * ov[i][2] + ov[i][3] * ov[i][3];
;             so = wave_sum(so); const float inv = rsqrtf(so * (1.0f / DM) + EPS);
; #pragma unroll
;             for (int i = 0; i < 8; ++i) { const f32x4 xo = __builtin_nontemporal_load((const f32x4*)(xin + (size_t)row * DM + RP_OFF(i))); const f32x4 gp = *(const f32x4*)(g_post + RP_OFF(i));
;                 xv[i] = xo + ov[i] * inv * gp; }
;         }
; #pragma unroll
;         for (int i = 0; i < 8; ++i) { if (mode != 0) __builtin_nontemporal_store(xv[i], (f32x4*)(xres + (size_t)row * DM + RP_OFF(i)));
;             ss += xv[i][0] * xv[i][0] + xv[i][1] * xv[i][1] + xv[i][2] * xv[i][2] + xv[i][3] * xv[i][3]; }
.Lrp_go2:
	s_mov_b32 s8, 0
	v_lshlrev_b32_e32 v0, 16, v120
	v_and_b32_e32 v1, 0xffff0000, v120
	v_lshlrev_b32_e32 v2, 16, v121
	v_and_b32_e32 v3, 0xffff0000, v121
	v_lshlrev_b32_e32 v4, 16, v122
	v_and_b32_e32 v5, 0xffff0000, v122
	v_lshlrev_b32_e32 v6, 16, v123
	v_and_b32_e32 v7, 0xffff0000, v123
	v_lshlrev_b32_e32 v8, 16, v124
	v_and_b32_e32 v9, 0xffff0000, v124
	v_lshlrev_b32_e32 v10, 16, v125
	v_and_b32_e32 v11, 0xffff0000, v125
	v_lshlrev_b32_e32 v12, 16, v126
	v_and_b32_e32 v13, 0xffff0000, v126
	v_lshlrev_b32_e32 v14, 16, v127
	v_and_b32_e32 v15, 0xffff0000, v127
	v_lshlrev_b32_e32 v16, 16, v128
	v_and_b32_e32 v17, 0xffff0000, v128
	v_lshlrev_b32_e32 v18, 16, v129
	v_and_b32_e32 v19, 0xffff0000, v129
	v_lshlrev_b32_e32 v20, 16, v130
	v_and_b32_e32 v21, 0xffff0000, v130
	v_lshlrev_b32_e32 v22, 16, v131
	v_and_b32_e32 v23, 0xffff0000, v131
	v_lshlrev_b32_e32 v24, 16, v132
	v_and_b32_e32 v25, 0xffff0000, v132
	v_lshlrev_b32_e32 v26, 16, v133
	v_and_b32_e32 v27, 0xffff0000, v133
	v_lshlrev_b32_e32 v28, 16, v134
	v_and_b32_e32 v29, 0xffff0000, v134
	v_lshlrev_b32_e32 v30, 16, v135
	v_and_b32_e32 v31, 0xffff0000, v135
	v_mul_f32_e32 v36, v0, v0
	v_mul_f32_e32 v37, v1, v1
	v_mul_f32_e32 v38, v2, v2
	v_mul_f32_e32 v39, v3, v3
	v_fmac_f32_e32 v36, v4, v4
	v_fmac_f32_e32 v37, v5, v5
	v_fmac_f32_e32 v38, v6, v6
	v_fmac_f32_e32 v39, v7, v7
	v_fmac_f32_e32 v36, v8, v8
	v_fmac_f32_e32 v37, v9, v9
	v_fmac_f32_e32 v38, v10, v10
	v_fmac_f32_e32 v39, v11, v11
	v_fmac_f32_e32 v36, v12, v12
	v_fmac_f32_e32 v37, v13, v13
	v_fmac_f32_e32 v38, v14, v14
	v_fmac_f32_e32 v39, v15, v15
	v_fmac_f32_e32 v36, v16, v16
	v_fmac_f32_e32 v37, v17, v17
	v_fmac_f32_e32 v38, v18, v18
	v_fmac_f32_e32 v39, v19, v19
	v_fmac_f32_e32 v36, v20, v20
	v_fmac_f32_e32 v37, v21, v21
	v_fmac_f32_e32 v38, v22, v22
	v_fmac_f32_e32 v39, v23, v23
	v_fmac_f32_e32 v36, v24, v24
	v_fmac_f32_e32 v37, v25, v25
	v_fmac_f32_e32 v38, v26, v26
	v_fmac_f32_e32 v39, v27, v27
	v_fmac_f32_e32 v36, v28, v28
	v_fmac_f32_e32 v37, v29, v29
	v_fmac_f32_e32 v38, v30, v30
	v_fmac_f32_e32 v39, v31, v31
	v_add_f32_e32 v36, v36, v37
	v_add_f32_e32 v38, v38, v39
	v_add_f32_e32 v58, v36, v38
	ds_bpermute_b32 v59, v68, v58
	s_waitcnt lgkmcnt(0)
	v_add_f32_e32 v58, v58, v59
	ds_bpermute_b32 v59, v69, v58
	s_waitcnt lgkmcnt(0)
	v_add_f32_e32 v58, v58, v59
	ds_bpermute_b32 v59, v70, v58
	s_waitcnt lgkmcnt(0)
	v_add_f32_e32 v58, v58, v59
	ds_bpermute_b32 v59, v71, v58
	s_waitcnt lgkmcnt(0)
	v_add_f32_e32 v58, v58, v59
	ds_bpermute_b32 v59, v61, v58
	s_waitcnt lgkmcnt(0)
	v_add_f32_e32 v58, v58, v59
	ds_bpermute_b32 v59, v62, v58
	s_waitcnt lgkmcnt(0)
	v_add_f32_e32 v58, v58, v59
	v_fmamk_f32 v60, v58, 0x3a000000, v252
	v_rsq_f32_e32 v60, v60
	s_nop 0
	v_mul_f32_e32 v0, v0, v60
	v_mul_f32_e32 v1, v1, v60
	v_mul_f32_e32 v2, v2, v60
	v_mul_f32_e32 v3, v3, v60
	v_mul_f32_e32 v4, v4, v60
	v_mul_f32_e32 v5, v5, v60
	v_mul_f32_e32 v6, v6, v60
	v_mul_f32_e32 v7, v7, v60
	v_mul_f32_e32 v8, v8, v60
	v_mul_f32_e32 v9, v9, v60
	v_mul_f32_e32 v10, v10, v60
	v_mul_f32_e32 v11, v11, v60
	v_mul_f32_e32 v12, v12, v60
	v_mul_f32_e32 v13, v13, v60
	v_mul_f32_e32 v14, v14, v60
	v_mul_f32_e32 v15, v15, v60
	v_mul_f32_e32 v16, v16, v60
	v_mul_f32_e32 v17, v17, v60
	v_mul_f32_e32 v18, v18, v60
	v_mul_f32_e32 v19, v19, v60
	v_mul_f32_e32 v20, v20, v60
	v_mul_f32_e32 v21, v21, v60
	v_mul_f32_e32 v22, v22, v60
	v_mul_f32_e32 v23, v23, v60
	v_mul_f32_e32 v24, v24, v60
	v_mul_f32_e32 v25, v25, v60
	v_mul_f32_e32 v26, v26, v60
	v_mul_f32_e32 v27, v27, v60
	v_mul_f32_e32 v28, v28, v60
	v_mul_f32_e32 v29, v29, v60
	v_mul_f32_e32 v30, v30, v60
	v_mul_f32_e32 v31, v31, v60
	v_fmac_f32_e32 v136, v178, v0
	v_fmac_f32_e32 v137, v179, v1
	v_fmac_f32_e32 v138, v180, v2
	v_fmac_f32_e32 v139, v181, v3
	v_fmac_f32_e32 v140, v182, v4
	v_fmac_f32_e32 v141, v183, v5
	v_fmac_f32_e32 v142, v184, v6
	v_fmac_f32_e32 v143, v185, v7
	v_fmac_f32_e32 v144, v186, v8
	v_fmac_f32_e32 v145, v187, v9
	v_fmac_f32_e32 v146, v188, v10
	v_fmac_f32_e32 v147, v189, v11
	v_fmac_f32_e32 v148, v190, v12
	v_fmac_f32_e32 v149, v191, v13
	v_fmac_f32_e32 v150, v192, v14
	v_fmac_f32_e32 v151, v193, v15
	v_fmac_f32_e32 v152, v194, v16
	v_fmac_f32_e32 v153, v195, v17
	v_fmac_f32_e32 v154, v196, v18
	v_fmac_f32_e32 v155, v197, v19
	v_fmac_f32_e32 v156, v198, v20
	v_fmac_f32_e32 v157, v199, v21
	v_fmac_f32_e32 v158, v200, v22
	v_fmac_f32_e32 v159, v201, v23
	v_fmac_f32_e32 v160, v202, v24
	v_fmac_f32_e32 v161, v203, v25
	v_fmac_f32_e32 v162, v204, v26
	v_fmac_f32_e32 v163, v205, v27
	v_fmac_f32_e32 v164, v206, v28
	v_fmac_f32_e32 v165, v207, v29
	v_fmac_f32_e32 v166, v208, v30
	v_fmac_f32_e32 v167, v209, v31
	v_lshl_add_u64 v[34:35], v[56:57], 0, s[16:17]
	global_store_dwordx4 v[56:57], v[136:139], off offset:0 nt
	global_store_dwordx4 v[56:57], v[140:143], off offset:16 nt
	global_store_dwordx4 v[56:57], v[144:147], off offset:2048 nt
	global_store_dwordx4 v[56:57], v[148:151], off offset:2064 nt
	global_store_dwordx4 v[34:35], v[152:155], off offset:0 nt
	global_store_dwordx4 v[34:35], v[156:159], off offset:16 nt
	global_store_dwordx4 v[34:35], v[160:163], off offset:2048 nt
	global_store_dwordx4 v[34:35], v[164:167], off offset:2064 nt
	v_lshl_add_u64 v[56:57], v[56:57], 0, s[72:73]
	s_andn2_b64 vcc, exec, s[10:11]
	s_cbranch_vccnz .Lrp_nopre2
; __device__ __forceinline__ u32x4 pack8(f32x4 a, f32x4 b) { u32x4 r; r[0] = cvt_pk_bf16(a[0], a[1]); r[1] = cvt_pk_bf16(a[2], a[3]); r[2] = cvt_pk_bf16(b[0], b[1]); r[3] = cvt_pk_bf16(b[2], b[3]); return r; }
; __device__ __forceinline__ void rowpass(int wv, const float* xin, const bf16_t* outb, const float* g_post, const float* g_pre_next, float* xres, bf16_t* xn, int mode) { LIDS
;     ...
;         if (g_pre_next) {
;             ss = wave_sum(ss); const float inv = rsqrtf(ss * (1.0f / DM) + EPS);
; #pragma unroll
;             for (int ip = 0; ip < 4; ++ip) { const f32x4 g0 = *(const f32x4*)(g_pre_next + RP_OFF(2 * ip)), g1 = *(const f32x4*)(g_pre_next + RP_OFF(2 * ip + 1));
;                 const f32x4 y0 = xv[2 * ip] * inv * g0, y1 = xv[2 * ip + 1] * inv * g1;
;                 *(u32x4*)(xn + (size_t)row * DM + ip * 512 + lane * 8) = pack8(y0, y1); }
;         }
	v_mul_f32_e32 v36, v136, v136
	v_mul_f32_e32 v37, v137, v137
	v_mul_f32_e32 v38, v138, v138
	v_mul_f32_e32 v39, v139, v139
	v_fmac_f32_e32 v36, v140, v140
	v_fmac_f32_e32 v37, v141, v141
	v_fmac_f32_e32 v38, v142, v142
	v_fmac_f32_e32 v39, v143, v143
	v_fmac_f32_e32 v36, v144, v144
	v_fmac_f32_e32 v37, v145, v145
	v_fmac_f32_e32 v38, v146, v146
	v_fmac_f32_e32 v39, v147, v147
	v_fmac_f32_e32 v36, v148, v148
	v_fmac_f32_e32 v37, v149, v149
	v_fmac_f32_e32 v38, v150, v150
	v_fmac_f32_e32 v39, v151, v151
	v_fmac_f32_e32 v36, v152, v152
	v_fmac_f32_e32 v37, v153, v153
	v_fmac_f32_e32 v38, v154, v154
	v_fmac_f32_e32 v39, v155, v155
	v_fmac_f32_e32 v36, v156, v156
	v_fmac_f32_e32 v37, v157, v157
	v_fmac_f32_e32 v38, v158, v158
	v_fmac_f32_e32 v39, v159, v159
	v_fmac_f32_e32 v36, v160, v160
	v_fmac_f32_e32 v37, v161, v161
	v_fmac_f32_e32 v38, v162, v162
	v_fmac_f32_e32 v39, v163, v163
	v_fmac_f32_e32 v36, v164, v164
	v_fmac_f32_e32 v37, v165, v165
	v_fmac_f32_e32 v38, v166, v166
	v_fmac_f32_e32 v39, v167, v167
	v_add_f32_e32 v36, v36, v37
	v_add_f32_e32 v38, v38, v39
	v_add_f32_e32 v58, v36, v38
	ds_bpermute_b32 v59, v68, v58
	s_waitcnt lgkmcnt(0)
	v_add_f32_e32 v58, v58, v59
	ds_bpermute_b32 v59, v69, v58
	s_waitcnt lgkmcnt(0)
	v_add_f32_e32 v58, v58, v59
	ds_bpermute_b32 v59, v70, v58
	s_waitcnt lgkmcnt(0)
	v_add_f32_e32 v58, v58, v59
	ds_bpermute_b32 v59, v71, v58
	s_waitcnt lgkmcnt(0)
	v_add_f32_e32 v58, v58, v59
	ds_bpermute_b32 v59, v61, v58
	s_waitcnt lgkmcnt(0)
	v_add_f32_e32 v58, v58, v59
	ds_bpermute_b32 v59, v62, v58
	s_waitcnt lgkmcnt(0)
	v_add_f32_e32 v58, v58, v59
	v_fmamk_f32 v60, v58, 0x3a000000, v252
	v_rsq_f32_e32 v60, v60
	s_nop 0
	v_mul_f32_e32 v168, v136, v60
	v_mul_f32_e32 v169, v137, v60
	v_mul_f32_e32 v170, v138, v60
	v_mul_f32_e32 v171, v139, v60
	v_mul_f32_e32 v172, v140, v60
	v_mul_f32_e32 v173, v141, v60
	v_mul_f32_e32 v174, v142, v60
	v_mul_f32_e32 v175, v143, v60
	v_mul_f32_e32 v168, v168, v218
	v_mul_f32_e32 v169, v169, v219
	v_mul_f32_e32 v170, v170, v220
	v_mul_f32_e32 v171, v171, v221
	v_mul_f32_e32 v172, v172, v222
	v_mul_f32_e32 v173, v173, v223
	v_mul_f32_e32 v174, v174, v224
	v_mul_f32_e32 v175, v175, v225
	v_cvt_pk_bf16_f32 v120, v168, v169
	v_cvt_pk_bf16_f32 v121, v170, v171
	v_cvt_pk_bf16_f32 v122, v172, v173
	v_cvt_pk_bf16_f32 v123, v174, v175
	v_mul_f32_e32 v168, v144, v60
	v_mul_f32_e32 v169, v145, v60
	v_mul_f32_e32 v170, v146, v60
	v_mul_f32_e32 v171, v147, v60
	v_mul_f32_e32 v172, v148, v60
	v_mul_f32_e32 v173, v149, v60
	v_mul_f32_e32 v174, v150, v60
	v_mul_f32_e32 v175, v151, v60
	v_mul_f32_e32 v168, v168, v226
	v_mul_f32_e32 v169, v169, v227
	v_mul_f32_e32 v170, v170, v228
	v_mul_f32_e32 v171, v171, v229
	v_mul_f32_e32 v172, v172, v230
	v_mul_f32_e32 v173, v173, v231
	v_mul_f32_e32 v174, v174, v232
	v_mul_f32_e32 v175, v175, v233
	v_cvt_pk_bf16_f32 v124, v168, v169
	v_cvt_pk_bf16_f32 v125, v170, v171
	v_cvt_pk_bf16_f32 v126, v172, v173
	v_cvt_pk_bf16_f32 v127, v174, v175
	v_mul_f32_e32 v168, v152, v60
	v_mul_f32_e32 v169, v153, v60
	v_mul_f32_e32 v170, v154, v60
	v_mul_f32_e32 v171, v155, v60
	v_mul_f32_e32 v172, v156, v60
	v_mul_f32_e32 v173, v157, v60
	v_mul_f32_e32 v174, v158, v60
	v_mul_f32_e32 v175, v159, v60
	v_mul_f32_e32 v168, v168, v234
	v_mul_f32_e32 v169, v169, v235
	v_mul_f32_e32 v170, v170, v236
	v_mul_f32_e32 v171, v171, v237
	v_mul_f32_e32 v172, v172, v238
	v_mul_f32_e32 v173, v173, v239
	v_mul_f32_e32 v174, v174, v240
	v_mul_f32_e32 v175, v175, v241
	v_cvt_pk_bf16_f32 v128, v168, v169
	v_cvt_pk_bf16_f32 v129, v170, v171
	v_cvt_pk_bf16_f32 v130, v172, v173
	v_cvt_pk_bf16_f32 v131, v174, v175
	v_mul_f32_e32 v168, v160, v60
	v_mul_f32_e32 v169, v161, v60
	v_mul_f32_e32 v170, v162, v60
	v_mul_f32_e32 v171, v163, v60
	v_mul_f32_e32 v172, v164, v60
	v_mul_f32_e32 v173, v165, v60
	v_mul_f32_e32 v174, v166, v60
	v_mul_f32_e32 v175, v167, v60
	v_mul_f32_e32 v168, v168, v242
	v_mul_f32_e32 v169, v169, v243
	v_mul_f32_e32 v170, v170, v244
	v_mul_f32_e32 v171, v171, v245
	v_mul_f32_e32 v172, v172, v246
	v_mul_f32_e32 v173, v173, v247
	v_mul_f32_e32 v174, v174, v248
	v_mul_f32_e32 v175, v175, v249
	v_cvt_pk_bf16_f32 v132, v168, v169
	v_cvt_pk_bf16_f32 v133, v170, v171
	v_cvt_pk_bf16_f32 v134, v172, v173
	v_cvt_pk_bf16_f32 v135, v174, v175
	global_store_dwordx4 v[32:33], v[120:123], off offset:0
	global_store_dwordx4 v[32:33], v[124:127], off offset:1024
	global_store_dwordx4 v[32:33], v[128:131], off offset:2048
	global_store_dwordx4 v[32:33], v[132:135], off offset:3072
	v_lshl_add_u64 v[32:33], v[32:33], 0, s[62:63]
; #define LAS __attribute__((address_space(3)))
; #define LIDS const int tid_l = TID(), bid_l = BID(), gdim_l = GDIM(); (void)tid_l; (void)bid_l; (void)gdim_l;
; __device__ __forceinline__ void rowpass(int wv, const float* xin, const bf16_t* outb, const float* g_post, const float* g_pre_next, float* xres, bf16_t* xn, int mode) { LIDS
;     ...
;     for (int row = bid_l * 8 + wid; row < SEQ; row += gdim_l * 8) {
; __device__ __forceinline__ void prep_layer(int wv, const Params& p, int layer, LAS unsigned char* lds) { LIDS
;     unsigned char* ws = p.ws; LAS float* tl = (LAS float*)lds;
;     const float* w_in = p.w_in + (size_t)layer * DM * NIN_REAL; const float* w_uq = p.w_uq + (size_t)layer * 512 * 1536; const float* w_ukv = p.w_ukv + (size_t)layer * 256 * 2048;
;     const float* w_glu = p.w_glu + (size_t)layer * 1024 * 2048; const float* w_out = p.w_out + (size_t)layer * 2048 * 2048;
;     const float* g_pre = nullptr;
;     const float* g_q = p.q_norm + layer * 512; const float* g_kv = p.kv_norm + layer * 256;
;     for (int t = bid_l; t < 976; t += gdim_l) {
;         if (t < 512) transpose_tile<0>(wv, w_in, NIN_REAL, DM, g_pre, (bf16_t*)(ws + OFF_WIN), t, 8, tl);
;         else if (t < 560) transpose_tile<1>(wv, w_uq, 1536, 512, g_q, (bf16_t*)(ws + OFF_WUQ), t - 512, 2, tl);
;         else if (t < 576) transpose_tile<2>(wv, w_ukv, 2048, 256, g_kv, (bf16_t*)(ws + OFF_WK), t - 560, 1, tl);
;         else if (t < 592) transpose_tile<3>(wv, w_ukv, 2048, 256, g_kv, (bf16_t*)(ws + OFF_WV), t - 576, 1, tl);
;         else if (t < 720) transpose_tile<4>(wv, w_glu, 2048, 1024, nullptr, (bf16_t*)(ws + OFF_WGLU), t - 592, 4, tl);
;         else transpose_tile<5>(wv, w_out, 2048, 2048, nullptr, (bf16_t*)(ws + OFF_WOUT), t - 720, 8, tl);
;     }
.Lrp_nopre2:
	s_cmp_gt_i32 s0, s96
	s_cbranch_scc1 .Lrp_done
	s_branch .Lrp_loop
.Lrp_done:
	s_mov_b32 s92, 0x800000
.LBB0_228:
	s_or_b64 exec, exec, s[6:7]
	s_andn2_b64 vcc, exec, s[4:5]
	s_cbranch_vccnz .LBB0_325
	s_mov_b32 s0, s3
	s_mov_b32 s55, s2
	v_mbcnt_lo_u32_b32 v0, -1, 0
	v_mbcnt_hi_u32_b32 v0, -1, v0
	s_mov_b32 s57, s56
	s_cmpk_gt_i32 s55, 0x3cf
	s_cbranch_scc1 .LBB0_325
	v_readlane_b32 s76, v254, 8
	s_mul_i32 s4, s68, 0x1e80000
	v_readlane_b32 s84, v254, 16
	s_mul_hi_i32 s0, s68, 0x1e80000
	v_readlane_b32 s85, v254, 17
	s_add_u32 s4, s84, s4
	v_readlane_b32 s88, v254, 20
	s_addc_u32 s5, s85, s0
	s_mul_i32 s6, s68, 0x300000
	v_readlane_b32 s89, v254, 21
	s_mul_hi_i32 s0, s68, 0x300000
	s_add_u32 s6, s88, s6
	s_addc_u32 s7, s89, s0
	s_lshl_b64 s[8:9], s[68:69], 21
	s_add_u32 s8, s36, s8
	v_readlane_b32 s16, v254, 30
	s_addc_u32 s9, s37, s9
	s_lshl_b64 s[10:11], s[68:69], 23
	v_readlane_b32 s18, v254, 32
	v_readlane_b32 s19, v254, 33
	s_add_u32 s10, s18, s10
	v_readlane_b32 s20, v254, 34
	s_addc_u32 s11, s19, s11
	s_lshl_b64 s[12:13], s[68:69], 24
	v_readlane_b32 s21, v254, 35
	s_add_u32 s12, s20, s12
	v_readlane_b32 s17, v254, 31
	s_addc_u32 s13, s21, s13
	s_lshl_b32 s16, s68, 9
	s_ashr_i32 s17, s16, 31
	v_readlane_b32 s86, v254, 18
	s_lshl_b64 s[16:17], s[16:17], 2
	v_readlane_b32 s87, v254, 19
	s_add_u32 s62, s86, s16
	s_addc_u32 s63, s87, s17
	s_lshl_b32 s16, s68, 8
	s_ashr_i32 s17, s16, 31
	v_readlane_b32 s90, v254, 22
	s_lshl_b64 s[16:17], s[16:17], 2
	v_readlane_b32 s91, v254, 23
	s_add_u32 s72, s90, s16
	v_readlane_b32 s78, v254, 10
	s_addc_u32 s73, s91, s17
	s_lshl_b32 s0, s55, 3
	s_add_i32 s78, s0, 0xffffe980
	s_lshl_b32 s0, s55, 4
	v_readlane_b32 s22, v254, 36
	v_readlane_b32 s23, v254, 37
	s_add_i32 s84, s0, 0xffffdb00
	s_lshl_b32 s0, s55, 7
	v_readlane_b32 s79, v254, 11
	s_add_i32 s86, s0, 0xfffee000
	s_lshl_b32 s16, s55, 6
	s_add_i32 s90, s0, 0xfffee800
	s_lshl_b32 s0, s55, 5
	v_readlane_b32 s20, v253, 22
	v_readlane_b32 s22, v253, 24
	v_readlane_b32 s24, v253, 26
	s_lshl_b32 s58, s55, 8
	s_lshl_b32 s59, s57, 8
	s_lshl_b32 s79, s57, 3
	s_lshl_b32 s85, s57, 4
	s_lshl_b32 s87, s57, 7
	s_add_i32 s88, s16, 0xffff7000
	s_lshl_b32 s89, s57, 6
	s_add_i32 s91, s0, 0xffffc000
	s_lshl_b32 s94, s57, 5
	v_readlane_b32 s21, v253, 23
	v_readlane_b32 s23, v253, 25
	v_readlane_b32 s25, v253, 27
	s_mov_b32 s26, 0x10000
	v_readlane_b32 s77, v254, 9
	v_readlane_b32 s80, v254, 12
	v_readlane_b32 s81, v254, 13
	v_readlane_b32 s82, v254, 14
	v_readlane_b32 s83, v254, 15
	s_branch .LBB0_233
